# sel fast steps: next-step decision and tile loads hoisted into MFMA tail; static prio for younger waves in attention
# speedup vs baseline: 1.0094x; 1.0094x over previous
.LBB0_1176:
	s_andn2_b64 vcc, exec, s[0:1]
	s_cbranch_vccnz .LBB0_2412
	v_readfirstlane_b32 s0, v0
	s_lshr_b32 s0, s0, 6
	s_cmp_ge_u32 s0, 4
	s_cbranch_scc0 .Lattn_noprio
	s_setprio 1
.Lattn_noprio:
	v_readlane_b32 s0, v253, 7
	v_mov_b32_e32 v1, v0
	v_readlane_b32 s1, v253, 8
	s_load_dword s0, s[0:1], 0x0
	s_waitcnt lgkmcnt(0)
	v_writelane_b32 v255, s0, 42
	s_nop 0
	v_readlane_b32 s0, v255, 0
	s_nop 1
	v_mov_b32_e32 v1, s0
	ds_read_b64 v[4:5], v1
	v_readlane_b32 s0, v255, 1
	s_nop 1
	v_mov_b32_e32 v1, s0
	ds_read_b64 v[6:7], v1
	s_waitcnt lgkmcnt(0)
	v_readfirstlane_b32 s0, v5
	s_nop 1
	v_writelane_b32 v255, s0, 44
	v_readfirstlane_b32 s0, v4
	s_nop 1
	v_writelane_b32 v255, s0, 45
	v_readfirstlane_b32 s0, v7
	s_nop 1
	v_writelane_b32 v255, s0, 46
	v_readlane_b32 s0, v254, 37
	v_readlane_b32 s1, v254, 38
	s_andn2_b64 vcc, exec, s[0:1]
	v_readfirstlane_b32 s0, v6
	s_nop 1
	v_writelane_b32 v255, s0, 47
	s_cbranch_vccnz .LBB0_1402
	v_readlane_b32 s1, v255, 45
	s_add_u32 s0, s1, 0x35000000
	v_writelane_b32 v255, s0, 48
	v_readlane_b32 s36, v253, 0
	v_readlane_b32 s0, v255, 44
	s_addc_u32 s2, s0, 0
	v_writelane_b32 v255, s2, 49
	s_add_u32 s2, s1, 0x35a00000
	v_writelane_b32 v255, s2, 50
	s_addc_u32 s2, s0, 0
	v_writelane_b32 v255, s2, 51
	s_add_u32 s2, s1, 0x16800000
	s_addc_u32 s3, s0, 0
	s_add_u32 s48, s1, 0x18800000
	v_writelane_b32 v255, s2, 52
	s_addc_u32 s49, s0, 0
	s_nop 0
	v_writelane_b32 v255, s3, 53
	s_add_u32 s2, s1, 0x14800000
	v_writelane_b32 v255, s2, 54
	s_addc_u32 s2, s0, 0
	v_writelane_b32 v255, s2, 55
	s_add_u32 s2, s1, 0x15800000
	v_writelane_b32 v255, s2, 56
	s_addc_u32 s2, s0, 0
	v_writelane_b32 v255, s2, 57
	s_add_u32 s2, s1, 0x18c00000
	s_addc_u32 s3, s0, 0
	v_writelane_b32 v255, s2, 58
	s_nop 1
	v_writelane_b32 v255, s3, 59
	v_writelane_b32 v255, s48, 60
	s_nop 1
	v_writelane_b32 v255, s49, 61
	s_branch .LBB0_1180

.Latt1a_entry:
	s_lshr_b32 s6, s9, 2
	s_and_b32 s6, s6, 0x3ffffff8
	s_waitcnt lgkmcnt(0)
	v_add3_u32 v251, s1, v205, v204
	v_add_u32_e32 v16, s6, v209
	s_add_i32 s1, s1, s0
	ds_read_b128 v[50:53], v251
	ds_read_b128 v[54:57], v251 offset:32
	ds_read_b128 v[58:61], v251 offset:64
	ds_read_b128 v[62:65], v251 offset:96
	ds_read_b128 v[66:69], v251 offset:4608
	ds_read_b128 v[70:73], v251 offset:4640
	ds_read_b128 v[74:77], v251 offset:4672
	ds_read_b128 v[78:81], v251 offset:4704
	ds_read_b64 v[16:17], v16
	v_add3_u32 v250, s1, v242, v244
	s_waitcnt lgkmcnt(8)
	v_mfma_f32_32x32x16_bf16 v[146:161], v[50:53], v[114:117], 0
	ds_read_b64_tr_b16 v[212:213], v250 offset:36864
	ds_read_b64_tr_b16 v[214:215], v250 offset:38400
	s_waitcnt lgkmcnt(9)
	v_mfma_f32_32x32x16_bf16 v[146:161], v[54:57], v[118:121], v[146:161]
	ds_read_b64_tr_b16 v[216:217], v250 offset:36928
	ds_read_b64_tr_b16 v[218:219], v250 offset:38464
	s_waitcnt lgkmcnt(10)
	v_mfma_f32_32x32x16_bf16 v[146:161], v[58:61], v[122:125], v[146:161]
	ds_read_b64_tr_b16 v[220:221], v250 offset:39936
	ds_read_b64_tr_b16 v[222:223], v250 offset:41472
	s_waitcnt lgkmcnt(11)
	v_mfma_f32_32x32x16_bf16 v[146:161], v[62:65], v[126:129], v[146:161]
	ds_read_b64_tr_b16 v[224:225], v250 offset:40000
	ds_read_b64_tr_b16 v[226:227], v250 offset:41536
	s_waitcnt lgkmcnt(8)
	v_and_b32_e32 v16, s28, v16
	v_and_b32_e32 v17, s29, v17
	v_cmp_eq_u64_e32 vcc, 0, v[16:17]
	s_nop 2
	v_mfma_f32_32x32x16_bf16 v[162:177], v[66:69], v[114:117], 0
	ds_read_b64_tr_b16 v[228:229], v250 offset:43008
	ds_read_b64_tr_b16 v[230:231], v250 offset:44544
	v_exp_f32_e32 v8, v146
	v_exp_f32_e32 v9, v147
	v_exp_f32_e32 v10, v148
	v_exp_f32_e32 v11, v149
	v_exp_f32_e32 v12, v150
	v_exp_f32_e32 v13, v151
	v_exp_f32_e32 v14, v152
	v_exp_f32_e32 v15, v153
	v_cvt_pk_bf16_f32 v178, v8, v9
	v_cvt_pk_bf16_f32 v179, v10, v11
	v_cvt_pk_bf16_f32 v180, v12, v13
	v_mfma_f32_32x32x16_bf16 v[162:177], v[70:73], v[118:121], v[162:177]
	ds_read_b64_tr_b16 v[232:233], v250 offset:43072
	ds_read_b64_tr_b16 v[234:235], v250 offset:44608
	v_cvt_pk_bf16_f32 v181, v14, v15
	v_add_f32_e32 v8, v8, v9
	v_add_f32_e32 v10, v10, v11
	v_add_f32_e32 v12, v12, v13
	v_add_f32_e32 v14, v14, v15
	v_add_f32_e32 v8, v8, v10
	v_add_f32_e32 v12, v12, v14
	v_add_f32_e32 v202, v8, v12
	v_cndmask_b32_e64 v178, v178, 0, vcc
	v_cndmask_b32_e64 v179, v179, 0, vcc
	v_cndmask_b32_e64 v180, v180, 0, vcc
	v_cndmask_b32_e64 v181, v181, 0, vcc
	v_mfma_f32_32x32x16_bf16 v[162:177], v[74:77], v[122:125], v[162:177]
	ds_read_b64_tr_b16 v[236:237], v250 offset:46080
	ds_read_b64_tr_b16 v[238:239], v250 offset:47616
	v_exp_f32_e32 v8, v154
	v_exp_f32_e32 v9, v155
	v_exp_f32_e32 v10, v156
	v_exp_f32_e32 v11, v157
	v_exp_f32_e32 v12, v158
	v_exp_f32_e32 v13, v159
	v_exp_f32_e32 v14, v160
	v_exp_f32_e32 v15, v161
	v_cvt_pk_bf16_f32 v182, v8, v9
	v_cvt_pk_bf16_f32 v183, v10, v11
	v_cvt_pk_bf16_f32 v184, v12, v13
	v_cvt_pk_bf16_f32 v185, v14, v15
	v_mfma_f32_32x32x16_bf16 v[162:177], v[78:81], v[126:129], v[162:177]
	ds_read_b64_tr_b16 v[4:5], v250 offset:46144
	s_waitcnt lgkmcnt(11)
	ds_read_b64_tr_b16 v[6:7], v250 offset:47680
	v_add_f32_e32 v8, v8, v9
	v_add_f32_e32 v10, v10, v11
	v_add_f32_e32 v12, v12, v13
	v_add_f32_e32 v14, v14, v15
	v_add_f32_e32 v8, v8, v10
	v_add_f32_e32 v12, v12, v14
	v_add_f32_e32 v8, v8, v12
	v_add_f32_e32 v202, v202, v8
	v_cndmask_b32_e64 v182, v182, 0, vcc
	v_cndmask_b32_e64 v183, v183, 0, vcc
	v_cndmask_b32_e64 v184, v184, 0, vcc
	v_cndmask_b32_e64 v185, v185, 0, vcc
	v_mfma_f32_32x32x16_bf16 v[18:33], v[212:215], v[178:181], v[18:33]
	v_exp_f32_e32 v8, v162
	v_exp_f32_e32 v9, v163
	v_exp_f32_e32 v10, v164
	v_exp_f32_e32 v11, v165
	v_exp_f32_e32 v12, v166
	v_exp_f32_e32 v13, v167
	v_exp_f32_e32 v14, v168
	v_exp_f32_e32 v15, v169
	v_cvt_pk_bf16_f32 v186, v8, v9
	v_cvt_pk_bf16_f32 v187, v10, v11
	v_cvt_pk_bf16_f32 v188, v12, v13
	v_cvt_pk_bf16_f32 v189, v14, v15
	v_mfma_f32_32x32x16_bf16 v[34:49], v[216:219], v[178:181], v[34:49]
	s_xor_b32 s0, s23, 1
	s_mul_i32 s1, s0, 0x4800
	s_mulk_i32 s0, 0x6000
	v_add_u32_e32 v207, s1, v206
	s_waitcnt vmcnt(2)
	ds_write_b128 v207, v[134:137]
	ds_write_b128 v207, v[130:133] offset:16
	v_add_f32_e32 v8, v8, v9
	v_add_f32_e32 v10, v10, v11
	v_add_f32_e32 v12, v12, v13
	v_add_f32_e32 v14, v14, v15
	v_add_f32_e32 v8, v8, v10
	v_add_f32_e32 v12, v12, v14
	v_add_f32_e32 v8, v8, v12
	v_add_f32_e32 v202, v202, v8
	v_cndmask_b32_e64 v186, v186, 0, vcc
	v_cndmask_b32_e64 v187, v187, 0, vcc
	v_cndmask_b32_e64 v188, v188, 0, vcc
	v_cndmask_b32_e64 v189, v189, 0, vcc
	s_waitcnt lgkmcnt(12)
	v_mfma_f32_32x32x16_bf16 v[18:33], v[220:223], v[182:185], v[18:33]
	v_exp_f32_e32 v8, v170
	v_exp_f32_e32 v9, v171
	v_exp_f32_e32 v10, v172
	v_exp_f32_e32 v11, v173
	v_exp_f32_e32 v12, v174
	v_exp_f32_e32 v13, v175
	v_exp_f32_e32 v14, v176
	v_exp_f32_e32 v15, v177
	v_cvt_pk_bf16_f32 v190, v8, v9
	v_cvt_pk_bf16_f32 v191, v10, v11
	v_cvt_pk_bf16_f32 v192, v12, v13
	v_cvt_pk_bf16_f32 v193, v14, v15
	s_waitcnt lgkmcnt(10)
	v_mfma_f32_32x32x16_bf16 v[34:49], v[224:227], v[182:185], v[34:49]
	v_add_u32_e32 v207, s0, v208
	s_waitcnt vmcnt(0)
	ds_write_b128 v207, v[142:145] offset:36864
	ds_write_b128 v207, v[138:141] offset:36880
	v_add_f32_e32 v8, v8, v9
	v_add_f32_e32 v10, v10, v11
	v_add_f32_e32 v12, v12, v13
	v_add_f32_e32 v14, v14, v15
	v_add_f32_e32 v8, v8, v10
	v_add_f32_e32 v12, v12, v14
	v_add_f32_e32 v8, v8, v12
	v_add_f32_e32 v202, v202, v8
	v_cndmask_b32_e64 v190, v190, 0, vcc
	v_cndmask_b32_e64 v191, v191, 0, vcc
	v_cndmask_b32_e64 v192, v192, 0, vcc
	v_cndmask_b32_e64 v193, v193, 0, vcc
	s_waitcnt lgkmcnt(10)
	v_mfma_f32_32x32x16_bf16 v[18:33], v[228:231], v[186:189], v[18:33]
	v_cndmask_b32_e64 v202, v202, 0, vcc
	v_add_f32_e32 v252, v2, v202
	v_mov_b32_e32 v2, v252
	s_waitcnt lgkmcnt(8)
	v_mfma_f32_32x32x16_bf16 v[34:49], v[232:235], v[186:189], v[34:49]
	s_waitcnt lgkmcnt(0)
	s_barrier
	v_mov_b32_e32 v16, v252
	s_nop 1
	s_add_i32 s22, s22, 2
	s_add_i32 s9, s9, 1
	v_add_u32_e32 v246, 0x80, v246
	s_cmp_lt_u32 s9, s17
	s_cselect_b64 s[24:25], -1, 0
	s_cbranch_scc0 .Lnx_a1a
	v_min_i32_e32 v240, 0x1fff, v246
	v_ashrrev_i32_e32 v241, 31, v240
	v_lshlrev_b64 v[240:241], 10, v[240:241]
	v_lshl_add_u64 v[240:241], v[210:211], 0, v[240:241]
	global_load_dwordx4 v[130:133], v[240:241], off offset:16
	global_load_dwordx4 v[134:137], v[240:241], off
	global_load_dwordx4 v[138:141], v[240:241], off offset:528
	global_load_dwordx4 v[142:145], v[240:241], off offset:512
.Lnx_a1a:
	v_mfma_f32_32x32x16_bf16 v[18:33], v[236:239], v[190:193], v[18:33]
	v_permlane32_swap_b32_e32 v2, v16
	v_max_f32_e32 v16, v16, v16
	s_add_i32 s23, s22, 1
	s_cmp_lt_u32 s9, 32
	s_mov_b32 s6, 62
	s_cselect_b32 s1, s33, s16
	s_cselect_b32 s0, s37, s8
	s_cmp_ge_u32 s23, s20
	s_mov_b32 s7, 63
	s_cselect_b64 s[10:11], -1, 0
	s_and_b64 s[6:7], s[22:23], s[6:7]
	s_lshl_b64 s[28:29], 1, s6
	s_lshl_b64 s[26:27], 1, s7
	s_and_b64 s[6:7], s[28:29], s[0:1]
	s_cmp_eq_u64 s[6:7], 0
	s_cselect_b64 vcc, -1, 0
	s_and_b64 s[34:35], s[26:27], s[0:1]
	s_cmp_eq_u64 s[34:35], 0
	s_cselect_b64 s[0:1], -1, 0
	s_or_b64 s[0:1], vcc, s[0:1]
	s_or_b64 s[0:1], s[0:1], s[10:11]
	v_mfma_f32_32x32x16_bf16 v[34:49], v[4:7], v[190:193], v[34:49]
	v_max_f32_e32 v2, v2, v2
	v_max_f32_e32 v2, v2, v16
	v_cmp_lt_f32_e32 vcc, s15, v2
	s_cbranch_vccnz .Lsel_shift_h
	s_cmp_eq_u32 s31, s22
	s_cbranch_scc1 .Lsel_fast_exit
	v_mov_b32_e32 v2, v252
	s_and_b32 s23, s9, 1
	s_cmp_eq_u64 s[0:1], 0
	s_mul_i32 s1, s23, 0x4800
	s_mul_i32 s0, s23, 0x1800
	s_cbranch_scc1 .Latt2_entry
	s_cmp_lg_u64 s[10:11], 0
	s_cbranch_scc1 .Lsel_generic
	s_cmp_lg_u64 s[6:7], 0
	s_cbranch_scc1 .Latt1a_entry
	s_cmp_lg_u64 s[34:35], 0
	s_cbranch_scc1 .Latt1b_entry
	s_branch .Lsel_none

.Latt1b_entry:
	s_lshr_b32 s6, s9, 2
	s_and_b32 s6, s6, 0x3ffffff8
	s_waitcnt lgkmcnt(0)
	v_add3_u32 v251, s1, v205, v204
	v_add_u32_e32 v16, s6, v209
	s_add_i32 s1, s1, s0
	ds_read_b128 v[50:53], v251 offset:9216
	ds_read_b128 v[54:57], v251 offset:9248
	ds_read_b128 v[58:61], v251 offset:9280
	ds_read_b128 v[62:65], v251 offset:9312
	ds_read_b128 v[66:69], v251 offset:13824
	ds_read_b128 v[70:73], v251 offset:13856
	ds_read_b128 v[74:77], v251 offset:13888
	ds_read_b128 v[78:81], v251 offset:13920
	ds_read_b64 v[16:17], v16
	v_add3_u32 v250, s1, v242, v244
	s_waitcnt lgkmcnt(8)
	v_mfma_f32_32x32x16_bf16 v[146:161], v[50:53], v[114:117], 0
	ds_read_b64_tr_b16 v[212:213], v250 offset:49152
	ds_read_b64_tr_b16 v[214:215], v250 offset:50688
	s_waitcnt lgkmcnt(9)
	v_mfma_f32_32x32x16_bf16 v[146:161], v[54:57], v[118:121], v[146:161]
	ds_read_b64_tr_b16 v[216:217], v250 offset:49216
	ds_read_b64_tr_b16 v[218:219], v250 offset:50752
	s_waitcnt lgkmcnt(10)
	v_mfma_f32_32x32x16_bf16 v[146:161], v[58:61], v[122:125], v[146:161]
	ds_read_b64_tr_b16 v[220:221], v250 offset:52224
	ds_read_b64_tr_b16 v[222:223], v250 offset:53760
	s_waitcnt lgkmcnt(11)
	v_mfma_f32_32x32x16_bf16 v[146:161], v[62:65], v[126:129], v[146:161]
	ds_read_b64_tr_b16 v[224:225], v250 offset:52288
	ds_read_b64_tr_b16 v[226:227], v250 offset:53824
	s_waitcnt lgkmcnt(8)
	v_and_b32_e32 v16, s26, v16
	v_and_b32_e32 v17, s27, v17
	v_cmp_eq_u64_e32 vcc, 0, v[16:17]
	s_nop 2
	v_mfma_f32_32x32x16_bf16 v[162:177], v[66:69], v[114:117], 0
	ds_read_b64_tr_b16 v[228:229], v250 offset:55296
	ds_read_b64_tr_b16 v[230:231], v250 offset:56832
	v_exp_f32_e32 v8, v146
	v_exp_f32_e32 v9, v147
	v_exp_f32_e32 v10, v148
	v_exp_f32_e32 v11, v149
	v_exp_f32_e32 v12, v150
	v_exp_f32_e32 v13, v151
	v_exp_f32_e32 v14, v152
	v_exp_f32_e32 v15, v153
	v_cvt_pk_bf16_f32 v178, v8, v9
	v_cvt_pk_bf16_f32 v179, v10, v11
	v_cvt_pk_bf16_f32 v180, v12, v13
	v_mfma_f32_32x32x16_bf16 v[162:177], v[70:73], v[118:121], v[162:177]
	ds_read_b64_tr_b16 v[232:233], v250 offset:55360
	ds_read_b64_tr_b16 v[234:235], v250 offset:56896
	v_cvt_pk_bf16_f32 v181, v14, v15
	v_add_f32_e32 v8, v8, v9
	v_add_f32_e32 v10, v10, v11
	v_add_f32_e32 v12, v12, v13
	v_add_f32_e32 v14, v14, v15
	v_add_f32_e32 v8, v8, v10
	v_add_f32_e32 v12, v12, v14
	v_add_f32_e32 v202, v8, v12
	v_cndmask_b32_e64 v178, v178, 0, vcc
	v_cndmask_b32_e64 v179, v179, 0, vcc
	v_cndmask_b32_e64 v180, v180, 0, vcc
	v_cndmask_b32_e64 v181, v181, 0, vcc
	v_mfma_f32_32x32x16_bf16 v[162:177], v[74:77], v[122:125], v[162:177]
	ds_read_b64_tr_b16 v[236:237], v250 offset:58368
	ds_read_b64_tr_b16 v[238:239], v250 offset:59904
	v_exp_f32_e32 v8, v154
	v_exp_f32_e32 v9, v155
	v_exp_f32_e32 v10, v156
	v_exp_f32_e32 v11, v157
	v_exp_f32_e32 v12, v158
	v_exp_f32_e32 v13, v159
	v_exp_f32_e32 v14, v160
	v_exp_f32_e32 v15, v161
	v_cvt_pk_bf16_f32 v182, v8, v9
	v_cvt_pk_bf16_f32 v183, v10, v11
	v_cvt_pk_bf16_f32 v184, v12, v13
	v_cvt_pk_bf16_f32 v185, v14, v15
	v_mfma_f32_32x32x16_bf16 v[162:177], v[78:81], v[126:129], v[162:177]
	ds_read_b64_tr_b16 v[4:5], v250 offset:58432
	s_waitcnt lgkmcnt(11)
	ds_read_b64_tr_b16 v[6:7], v250 offset:59968
	v_add_f32_e32 v8, v8, v9
	v_add_f32_e32 v10, v10, v11
	v_add_f32_e32 v12, v12, v13
	v_add_f32_e32 v14, v14, v15
	v_add_f32_e32 v8, v8, v10
	v_add_f32_e32 v12, v12, v14
	v_add_f32_e32 v8, v8, v12
	v_add_f32_e32 v202, v202, v8
	v_cndmask_b32_e64 v182, v182, 0, vcc
	v_cndmask_b32_e64 v183, v183, 0, vcc
	v_cndmask_b32_e64 v184, v184, 0, vcc
	v_cndmask_b32_e64 v185, v185, 0, vcc
	v_mfma_f32_32x32x16_bf16 v[18:33], v[212:215], v[178:181], v[18:33]
	v_exp_f32_e32 v8, v162
	v_exp_f32_e32 v9, v163
	v_exp_f32_e32 v10, v164
	v_exp_f32_e32 v11, v165
	v_exp_f32_e32 v12, v166
	v_exp_f32_e32 v13, v167
	v_exp_f32_e32 v14, v168
	v_exp_f32_e32 v15, v169
	v_cvt_pk_bf16_f32 v186, v8, v9
	v_cvt_pk_bf16_f32 v187, v10, v11
	v_cvt_pk_bf16_f32 v188, v12, v13
	v_cvt_pk_bf16_f32 v189, v14, v15
	v_mfma_f32_32x32x16_bf16 v[34:49], v[216:219], v[178:181], v[34:49]
	s_xor_b32 s0, s23, 1
	s_mul_i32 s1, s0, 0x4800
	s_mulk_i32 s0, 0x6000
	v_add_u32_e32 v207, s1, v206
	s_waitcnt vmcnt(2)
	ds_write_b128 v207, v[134:137]
	ds_write_b128 v207, v[130:133] offset:16
	v_add_f32_e32 v8, v8, v9
	v_add_f32_e32 v10, v10, v11
	v_add_f32_e32 v12, v12, v13
	v_add_f32_e32 v14, v14, v15
	v_add_f32_e32 v8, v8, v10
	v_add_f32_e32 v12, v12, v14
	v_add_f32_e32 v8, v8, v12
	v_add_f32_e32 v202, v202, v8
	v_cndmask_b32_e64 v186, v186, 0, vcc
	v_cndmask_b32_e64 v187, v187, 0, vcc
	v_cndmask_b32_e64 v188, v188, 0, vcc
	v_cndmask_b32_e64 v189, v189, 0, vcc
	s_waitcnt lgkmcnt(12)
	v_mfma_f32_32x32x16_bf16 v[18:33], v[220:223], v[182:185], v[18:33]
	v_exp_f32_e32 v8, v170
	v_exp_f32_e32 v9, v171
	v_exp_f32_e32 v10, v172
	v_exp_f32_e32 v11, v173
	v_exp_f32_e32 v12, v174
	v_exp_f32_e32 v13, v175
	v_exp_f32_e32 v14, v176
	v_exp_f32_e32 v15, v177
	v_cvt_pk_bf16_f32 v190, v8, v9
	v_cvt_pk_bf16_f32 v191, v10, v11
	v_cvt_pk_bf16_f32 v192, v12, v13
	v_cvt_pk_bf16_f32 v193, v14, v15
	s_waitcnt lgkmcnt(10)
	v_mfma_f32_32x32x16_bf16 v[34:49], v[224:227], v[182:185], v[34:49]
	v_add_u32_e32 v207, s0, v208
	s_waitcnt vmcnt(0)
	ds_write_b128 v207, v[142:145] offset:36864
	ds_write_b128 v207, v[138:141] offset:36880
	v_add_f32_e32 v8, v8, v9
	v_add_f32_e32 v10, v10, v11
	v_add_f32_e32 v12, v12, v13
	v_add_f32_e32 v14, v14, v15
	v_add_f32_e32 v8, v8, v10
	v_add_f32_e32 v12, v12, v14
	v_add_f32_e32 v8, v8, v12
	v_add_f32_e32 v202, v202, v8
	v_cndmask_b32_e64 v190, v190, 0, vcc
	v_cndmask_b32_e64 v191, v191, 0, vcc
	v_cndmask_b32_e64 v192, v192, 0, vcc
	v_cndmask_b32_e64 v193, v193, 0, vcc
	s_waitcnt lgkmcnt(10)
	v_mfma_f32_32x32x16_bf16 v[18:33], v[228:231], v[186:189], v[18:33]
	v_cndmask_b32_e64 v202, v202, 0, vcc
	v_add_f32_e32 v252, v2, v202
	v_mov_b32_e32 v2, v252
	s_waitcnt lgkmcnt(8)
	v_mfma_f32_32x32x16_bf16 v[34:49], v[232:235], v[186:189], v[34:49]
	s_waitcnt lgkmcnt(0)
	s_barrier
	v_mov_b32_e32 v16, v252
	s_nop 1
	s_add_i32 s22, s22, 2
	s_add_i32 s9, s9, 1
	v_add_u32_e32 v246, 0x80, v246
	s_cmp_lt_u32 s9, s17
	s_cselect_b64 s[24:25], -1, 0
	s_cbranch_scc0 .Lnx_a1b
	v_min_i32_e32 v240, 0x1fff, v246
	v_ashrrev_i32_e32 v241, 31, v240
	v_lshlrev_b64 v[240:241], 10, v[240:241]
	v_lshl_add_u64 v[240:241], v[210:211], 0, v[240:241]
	global_load_dwordx4 v[130:133], v[240:241], off offset:16
	global_load_dwordx4 v[134:137], v[240:241], off
	global_load_dwordx4 v[138:141], v[240:241], off offset:528
	global_load_dwordx4 v[142:145], v[240:241], off offset:512

.Lsel_shift_h:
	s_nop 0
	v_cndmask_b32_e32 v4, 0, v248, vcc
	v_cndmask_b32_e32 v2, 1.0, v249, vcc
	v_add_f32_e32 v243, v243, v4
	v_mul_f32_e32 v252, v252, v2
	v_pk_mul_f32 v[32:33], v[32:33], v[2:3] op_sel_hi:[1,0]
	v_pk_mul_f32 v[30:31], v[30:31], v[2:3] op_sel_hi:[1,0]
	v_pk_mul_f32 v[28:29], v[28:29], v[2:3] op_sel_hi:[1,0]
	v_pk_mul_f32 v[26:27], v[26:27], v[2:3] op_sel_hi:[1,0]
	v_pk_mul_f32 v[24:25], v[24:25], v[2:3] op_sel_hi:[1,0]
	v_pk_mul_f32 v[22:23], v[22:23], v[2:3] op_sel_hi:[1,0]
	v_pk_mul_f32 v[20:21], v[20:21], v[2:3] op_sel_hi:[1,0]
	v_pk_mul_f32 v[18:19], v[18:19], v[2:3] op_sel_hi:[1,0]
	v_pk_mul_f32 v[48:49], v[48:49], v[2:3] op_sel_hi:[1,0]
	v_pk_mul_f32 v[46:47], v[46:47], v[2:3] op_sel_hi:[1,0]
	v_pk_mul_f32 v[44:45], v[44:45], v[2:3] op_sel_hi:[1,0]
	v_pk_mul_f32 v[42:43], v[42:43], v[2:3] op_sel_hi:[1,0]
	v_pk_mul_f32 v[40:41], v[40:41], v[2:3] op_sel_hi:[1,0]
	v_pk_mul_f32 v[38:39], v[38:39], v[2:3] op_sel_hi:[1,0]
	v_pk_mul_f32 v[36:37], v[36:37], v[2:3] op_sel_hi:[1,0]
	v_pk_mul_f32 v[34:35], v[34:35], v[2:3] op_sel_hi:[1,0]
	v_mov_b32_e32 v2, v252
	s_branch .LBB0_1321

.Latt2_entry:
	s_lshr_b32 s6, s9, 2
	s_and_b32 s6, s6, 0x3ffffff8
	s_waitcnt lgkmcnt(0)
	v_add3_u32 v251, s1, v205, v204
	v_add_u32_e32 v16, s6, v209
	s_add_i32 s1, s1, s0
	ds_read_b128 v[50:53], v251
	ds_read_b128 v[54:57], v251 offset:32
	ds_read_b128 v[58:61], v251 offset:64
	ds_read_b128 v[62:65], v251 offset:96
	ds_read_b128 v[66:69], v251 offset:4608
	ds_read_b128 v[70:73], v251 offset:4640
	ds_read_b128 v[74:77], v251 offset:4672
	ds_read_b128 v[78:81], v251 offset:4704
	ds_read_b64 v[16:17], v16
	v_add3_u32 v250, s1, v242, v244
	s_waitcnt lgkmcnt(8)
	v_mfma_f32_32x32x16_bf16 v[146:161], v[50:53], v[114:117], 0
	ds_read_b128 v[82:85], v251 offset:9216
	ds_read_b128 v[86:89], v251 offset:9248
	s_waitcnt lgkmcnt(9)
	v_mfma_f32_32x32x16_bf16 v[146:161], v[54:57], v[118:121], v[146:161]
	ds_read_b128 v[90:93], v251 offset:9280
	ds_read_b128 v[94:97], v251 offset:9312
	s_waitcnt lgkmcnt(10)
	v_mfma_f32_32x32x16_bf16 v[146:161], v[58:61], v[122:125], v[146:161]
	ds_read_b128 v[98:101], v251 offset:13824
	ds_read_b128 v[102:105], v251 offset:13856
	s_waitcnt lgkmcnt(11)
	v_mfma_f32_32x32x16_bf16 v[146:161], v[62:65], v[126:129], v[146:161]
	ds_read_b128 v[106:109], v251 offset:13888
	ds_read_b128 v[110:113], v251 offset:13920
	s_waitcnt lgkmcnt(8)
	v_and_b32_e32 v240, s28, v16
	v_and_b32_e32 v241, s29, v17
	v_and_b32_e32 v16, s26, v16
	v_and_b32_e32 v17, s27, v17
	v_cmp_eq_u64_e32 vcc, 0, v[240:241]
	v_cmp_eq_u64_e64 s[6:7], 0, v[16:17]
	v_mfma_f32_32x32x16_bf16 v[162:177], v[66:69], v[114:117], 0
	ds_read_b64_tr_b16 v[212:213], v250 offset:36864
	ds_read_b64_tr_b16 v[214:215], v250 offset:38400
	v_exp_f32_e32 v8, v146
	v_exp_f32_e32 v9, v147
	v_exp_f32_e32 v10, v148
	v_exp_f32_e32 v11, v149
	v_exp_f32_e32 v12, v150
	v_exp_f32_e32 v13, v151
	v_exp_f32_e32 v14, v152
	v_mfma_f32_32x32x16_bf16 v[162:177], v[70:73], v[118:121], v[162:177]
	ds_read_b64_tr_b16 v[216:217], v250 offset:36928
	ds_read_b64_tr_b16 v[218:219], v250 offset:38464
	v_exp_f32_e32 v15, v153
	v_cvt_pk_bf16_f32 v178, v8, v9
	v_cvt_pk_bf16_f32 v179, v10, v11
	v_cvt_pk_bf16_f32 v180, v12, v13
	v_cvt_pk_bf16_f32 v181, v14, v15
	v_add_f32_e32 v8, v8, v9
	v_add_f32_e32 v10, v10, v11
	v_add_f32_e32 v12, v12, v13
	v_mfma_f32_32x32x16_bf16 v[162:177], v[74:77], v[122:125], v[162:177]
	ds_read_b64_tr_b16 v[220:221], v250 offset:39936
	ds_read_b64_tr_b16 v[222:223], v250 offset:41472
	v_add_f32_e32 v14, v14, v15
	v_add_f32_e32 v8, v8, v10
	v_add_f32_e32 v12, v12, v14
	v_add_f32_e32 v202, v8, v12
	v_cndmask_b32_e64 v178, v178, 0, vcc
	v_cndmask_b32_e64 v179, v179, 0, vcc
	v_cndmask_b32_e64 v180, v180, 0, vcc
	v_cndmask_b32_e64 v181, v181, 0, vcc
	v_mfma_f32_32x32x16_bf16 v[162:177], v[78:81], v[126:129], v[162:177]
	ds_read_b64_tr_b16 v[224:225], v250 offset:40000
	s_waitcnt lgkmcnt(11)
	ds_read_b64_tr_b16 v[226:227], v250 offset:41536
	v_exp_f32_e32 v8, v154
	v_exp_f32_e32 v9, v155
	v_exp_f32_e32 v10, v156
	v_exp_f32_e32 v11, v157
	v_exp_f32_e32 v12, v158
	v_exp_f32_e32 v13, v159
	v_exp_f32_e32 v14, v160
	v_exp_f32_e32 v15, v161
	v_mfma_f32_32x32x16_bf16 v[50:65], v[82:85], v[114:117], 0
	ds_read_b64_tr_b16 v[228:229], v250 offset:43008
	ds_read_b64_tr_b16 v[230:231], v250 offset:44544
	v_cvt_pk_bf16_f32 v182, v8, v9
	v_cvt_pk_bf16_f32 v183, v10, v11
	v_cvt_pk_bf16_f32 v184, v12, v13
	v_cvt_pk_bf16_f32 v185, v14, v15
	v_add_f32_e32 v8, v8, v9
	v_add_f32_e32 v10, v10, v11
	v_add_f32_e32 v12, v12, v13
	v_add_f32_e32 v14, v14, v15
	v_mfma_f32_32x32x16_bf16 v[50:65], v[86:89], v[118:121], v[50:65]
	ds_read_b64_tr_b16 v[232:233], v250 offset:43072
	s_waitcnt lgkmcnt(11)
	ds_read_b64_tr_b16 v[234:235], v250 offset:44608
	v_add_f32_e32 v8, v8, v10
	v_add_f32_e32 v12, v12, v14
	v_add_f32_e32 v8, v8, v12
	v_add_f32_e32 v202, v202, v8
	v_cndmask_b32_e64 v182, v182, 0, vcc
	v_cndmask_b32_e64 v183, v183, 0, vcc
	v_cndmask_b32_e64 v184, v184, 0, vcc
	v_cndmask_b32_e64 v185, v185, 0, vcc
	v_mfma_f32_32x32x16_bf16 v[50:65], v[90:93], v[122:125], v[50:65]
	ds_read_b64_tr_b16 v[236:237], v250 offset:46080
	ds_read_b64_tr_b16 v[238:239], v250 offset:47616
	v_exp_f32_e32 v8, v162
	v_exp_f32_e32 v9, v163
	v_exp_f32_e32 v10, v164
	v_exp_f32_e32 v11, v165
	v_exp_f32_e32 v12, v166
	v_exp_f32_e32 v13, v167
	v_exp_f32_e32 v14, v168
	v_exp_f32_e32 v15, v169
	v_mfma_f32_32x32x16_bf16 v[50:65], v[94:97], v[126:129], v[50:65]
	ds_read_b64_tr_b16 v[4:5], v250 offset:46144
	s_waitcnt lgkmcnt(11)
	ds_read_b64_tr_b16 v[6:7], v250 offset:47680
	v_cvt_pk_bf16_f32 v186, v8, v9
	v_cvt_pk_bf16_f32 v187, v10, v11
	v_cvt_pk_bf16_f32 v188, v12, v13
	v_cvt_pk_bf16_f32 v189, v14, v15
	v_add_f32_e32 v8, v8, v9
	v_add_f32_e32 v10, v10, v11
	v_add_f32_e32 v12, v12, v13
	v_add_f32_e32 v14, v14, v15
	v_mfma_f32_32x32x16_bf16 v[66:81], v[98:101], v[114:117], 0
	ds_read_b64_tr_b16 v[146:147], v250 offset:49152
	ds_read_b64_tr_b16 v[148:149], v250 offset:50688
	v_add_f32_e32 v8, v8, v10
	v_add_f32_e32 v12, v12, v14
	v_add_f32_e32 v8, v8, v12
	v_add_f32_e32 v202, v202, v8
	v_cndmask_b32_e64 v186, v186, 0, vcc
	v_cndmask_b32_e64 v187, v187, 0, vcc
	v_cndmask_b32_e64 v188, v188, 0, vcc
	v_cndmask_b32_e64 v189, v189, 0, vcc
	v_mfma_f32_32x32x16_bf16 v[66:81], v[102:105], v[118:121], v[66:81]
	ds_read_b64_tr_b16 v[150:151], v250 offset:49216
	s_waitcnt lgkmcnt(11)
	ds_read_b64_tr_b16 v[152:153], v250 offset:50752
	v_exp_f32_e32 v8, v170
	v_exp_f32_e32 v9, v171
	v_exp_f32_e32 v10, v172
	v_exp_f32_e32 v11, v173
	v_exp_f32_e32 v12, v174
	v_exp_f32_e32 v13, v175
	v_exp_f32_e32 v14, v176
	v_exp_f32_e32 v15, v177
	v_mfma_f32_32x32x16_bf16 v[66:81], v[106:109], v[122:125], v[66:81]
	ds_read_b64_tr_b16 v[154:155], v250 offset:52224
	ds_read_b64_tr_b16 v[156:157], v250 offset:53760
	v_cvt_pk_bf16_f32 v190, v8, v9
	v_cvt_pk_bf16_f32 v191, v10, v11
	v_cvt_pk_bf16_f32 v192, v12, v13
	v_cvt_pk_bf16_f32 v193, v14, v15
	v_add_f32_e32 v8, v8, v9
	v_add_f32_e32 v10, v10, v11
	v_add_f32_e32 v12, v12, v13
	v_add_f32_e32 v14, v14, v15
	v_mfma_f32_32x32x16_bf16 v[66:81], v[110:113], v[126:129], v[66:81]
	ds_read_b64_tr_b16 v[158:159], v250 offset:52288
	s_waitcnt lgkmcnt(11)
	ds_read_b64_tr_b16 v[160:161], v250 offset:53824
	v_add_f32_e32 v8, v8, v10
	v_add_f32_e32 v12, v12, v14
	v_add_f32_e32 v8, v8, v12
	v_add_f32_e32 v202, v202, v8
	v_cndmask_b32_e64 v190, v190, 0, vcc
	v_cndmask_b32_e64 v191, v191, 0, vcc
	v_cndmask_b32_e64 v192, v192, 0, vcc
	v_cndmask_b32_e64 v193, v193, 0, vcc
	v_mfma_f32_32x32x16_bf16 v[18:33], v[212:215], v[178:181], v[18:33]
	v_exp_f32_e32 v8, v50
	v_exp_f32_e32 v9, v51
	v_exp_f32_e32 v10, v52
	v_exp_f32_e32 v11, v53
	v_exp_f32_e32 v12, v54
	v_exp_f32_e32 v13, v55
	v_exp_f32_e32 v14, v56
	v_exp_f32_e32 v15, v57
	v_mfma_f32_32x32x16_bf16 v[34:49], v[216:219], v[178:181], v[34:49]
	ds_read_b64_tr_b16 v[162:163], v250 offset:55296
	ds_read_b64_tr_b16 v[164:165], v250 offset:56832
	v_cvt_pk_bf16_f32 v178, v8, v9
	v_cvt_pk_bf16_f32 v179, v10, v11
	v_cvt_pk_bf16_f32 v180, v12, v13
	v_cvt_pk_bf16_f32 v181, v14, v15
	v_add_f32_e32 v8, v8, v9
	v_add_f32_e32 v10, v10, v11
	v_add_f32_e32 v12, v12, v13
	v_add_f32_e32 v14, v14, v15
	v_mfma_f32_32x32x16_bf16 v[18:33], v[220:223], v[182:185], v[18:33]
	ds_read_b64_tr_b16 v[166:167], v250 offset:55360
	s_waitcnt lgkmcnt(11)
	ds_read_b64_tr_b16 v[168:169], v250 offset:56896
	v_add_f32_e32 v8, v8, v10
	v_add_f32_e32 v12, v12, v14
	v_add_f32_e32 v203, v8, v12
	v_cndmask_b32_e64 v178, v178, 0, s[6:7]
	v_cndmask_b32_e64 v179, v179, 0, s[6:7]
	v_cndmask_b32_e64 v180, v180, 0, s[6:7]
	v_cndmask_b32_e64 v181, v181, 0, s[6:7]
	v_exp_f32_e32 v8, v58
	v_mfma_f32_32x32x16_bf16 v[34:49], v[224:227], v[182:185], v[34:49]
	ds_read_b64_tr_b16 v[170:171], v250 offset:58368
	ds_read_b64_tr_b16 v[172:173], v250 offset:59904
	v_exp_f32_e32 v9, v59
	v_exp_f32_e32 v10, v60
	v_exp_f32_e32 v11, v61
	v_exp_f32_e32 v12, v62
	v_exp_f32_e32 v13, v63
	v_exp_f32_e32 v14, v64
	v_exp_f32_e32 v15, v65
	v_cvt_pk_bf16_f32 v182, v8, v9
	v_mfma_f32_32x32x16_bf16 v[18:33], v[228:231], v[186:189], v[18:33]
	ds_read_b64_tr_b16 v[174:175], v250 offset:58432
	s_waitcnt lgkmcnt(11)
	ds_read_b64_tr_b16 v[176:177], v250 offset:59968
	v_cvt_pk_bf16_f32 v183, v10, v11
	v_cvt_pk_bf16_f32 v184, v12, v13
	v_cvt_pk_bf16_f32 v185, v14, v15
	v_add_f32_e32 v8, v8, v9
	v_add_f32_e32 v10, v10, v11
	v_add_f32_e32 v12, v12, v13
	v_add_f32_e32 v14, v14, v15
	v_add_f32_e32 v8, v8, v10
	v_mfma_f32_32x32x16_bf16 v[34:49], v[232:235], v[186:189], v[34:49]
	s_xor_b32 s0, s23, 1
	s_mul_i32 s1, s0, 0x4800
	s_mulk_i32 s0, 0x6000
	v_add_u32_e32 v207, s1, v206
	s_waitcnt vmcnt(2)
	ds_write_b128 v207, v[134:137]
	ds_write_b128 v207, v[130:133] offset:16
	v_add_f32_e32 v12, v12, v14
	v_add_f32_e32 v8, v8, v12
	v_add_f32_e32 v203, v203, v8
	v_cndmask_b32_e64 v182, v182, 0, s[6:7]
	v_cndmask_b32_e64 v183, v183, 0, s[6:7]
	v_cndmask_b32_e64 v184, v184, 0, s[6:7]
	v_cndmask_b32_e64 v185, v185, 0, s[6:7]
	v_exp_f32_e32 v8, v66
	v_mfma_f32_32x32x16_bf16 v[18:33], v[236:239], v[190:193], v[18:33]
	v_exp_f32_e32 v9, v67
	v_exp_f32_e32 v10, v68
	v_exp_f32_e32 v11, v69
	v_exp_f32_e32 v12, v70
	v_exp_f32_e32 v13, v71
	v_exp_f32_e32 v14, v72
	v_exp_f32_e32 v15, v73
	v_cvt_pk_bf16_f32 v186, v8, v9
	v_mfma_f32_32x32x16_bf16 v[34:49], v[4:7], v[190:193], v[34:49]
	v_add_u32_e32 v207, s0, v208
	s_waitcnt vmcnt(0)
	ds_write_b128 v207, v[142:145] offset:36864
	s_waitcnt lgkmcnt(11)
	ds_write_b128 v207, v[138:141] offset:36880
	v_cvt_pk_bf16_f32 v187, v10, v11
	v_cvt_pk_bf16_f32 v188, v12, v13
	v_cvt_pk_bf16_f32 v189, v14, v15
	v_add_f32_e32 v8, v8, v9
	v_add_f32_e32 v10, v10, v11
	v_add_f32_e32 v12, v12, v13
	v_add_f32_e32 v14, v14, v15
	v_add_f32_e32 v8, v8, v10
	v_mfma_f32_32x32x16_bf16 v[18:33], v[146:149], v[178:181], v[18:33]
	v_add_f32_e32 v12, v12, v14
	v_add_f32_e32 v8, v8, v12
	v_add_f32_e32 v203, v203, v8
	v_cndmask_b32_e64 v186, v186, 0, s[6:7]
	v_cndmask_b32_e64 v187, v187, 0, s[6:7]
	v_cndmask_b32_e64 v188, v188, 0, s[6:7]
	v_cndmask_b32_e64 v189, v189, 0, s[6:7]
	v_exp_f32_e32 v8, v74
	v_mfma_f32_32x32x16_bf16 v[34:49], v[150:153], v[178:181], v[34:49]
	v_exp_f32_e32 v9, v75
	v_exp_f32_e32 v10, v76
	v_exp_f32_e32 v11, v77
	v_exp_f32_e32 v12, v78
	v_exp_f32_e32 v13, v79
	v_exp_f32_e32 v14, v80
	v_exp_f32_e32 v15, v81
	v_cvt_pk_bf16_f32 v190, v8, v9
	v_mfma_f32_32x32x16_bf16 v[18:33], v[154:157], v[182:185], v[18:33]
	s_waitcnt lgkmcnt(0)
	s_barrier
	v_cvt_pk_bf16_f32 v191, v10, v11
	v_cvt_pk_bf16_f32 v192, v12, v13
	v_cvt_pk_bf16_f32 v193, v14, v15
	v_add_f32_e32 v8, v8, v9
	v_add_f32_e32 v10, v10, v11
	v_add_f32_e32 v12, v12, v13
	v_add_f32_e32 v14, v14, v15
	v_add_f32_e32 v8, v8, v10
	v_mfma_f32_32x32x16_bf16 v[34:49], v[158:161], v[182:185], v[34:49]
	v_add_f32_e32 v12, v12, v14
	v_add_f32_e32 v8, v8, v12
	v_add_f32_e32 v203, v203, v8
	v_cndmask_b32_e64 v190, v190, 0, s[6:7]
	v_cndmask_b32_e64 v191, v191, 0, s[6:7]
	v_cndmask_b32_e64 v192, v192, 0, s[6:7]
	v_cndmask_b32_e64 v193, v193, 0, s[6:7]
	v_cndmask_b32_e64 v202, v202, 0, vcc
	v_mfma_f32_32x32x16_bf16 v[18:33], v[162:165], v[186:189], v[18:33]
	v_cndmask_b32_e64 v203, v203, 0, s[6:7]
	v_add_f32_e32 v202, v202, v203
	v_add_f32_e32 v252, v2, v202
	v_mov_b32_e32 v2, v252
	s_add_i32 s22, s22, 2
	s_add_i32 s9, s9, 1
	v_add_u32_e32 v246, 0x80, v246
	s_cmp_lt_u32 s9, s17
	s_cselect_b64 s[24:25], -1, 0
	s_cbranch_scc0 .Lnx_a2
	v_min_i32_e32 v240, 0x1fff, v246
	v_ashrrev_i32_e32 v241, 31, v240
	v_lshlrev_b64 v[240:241], 10, v[240:241]
	v_lshl_add_u64 v[240:241], v[210:211], 0, v[240:241]
	global_load_dwordx4 v[130:133], v[240:241], off offset:16
	global_load_dwordx4 v[134:137], v[240:241], off
	global_load_dwordx4 v[138:141], v[240:241], off offset:528
	global_load_dwordx4 v[142:145], v[240:241], off offset:512
.Lnx_a2:
	v_mfma_f32_32x32x16_bf16 v[34:49], v[166:169], v[186:189], v[34:49]
	v_mov_b32_e32 v4, v252
	s_nop 1
	v_permlane32_swap_b32_e32 v2, v4
	s_add_i32 s23, s22, 1
	s_cmp_lt_u32 s9, 32
	s_mov_b32 s6, 62
	s_cselect_b32 s1, s33, s16
	s_cselect_b32 s0, s37, s8
	s_cmp_ge_u32 s23, s20
	s_mov_b32 s7, 63
	s_cselect_b64 s[10:11], -1, 0
	s_and_b64 s[6:7], s[22:23], s[6:7]
	s_lshl_b64 s[28:29], 1, s6
	s_lshl_b64 s[26:27], 1, s7
	s_and_b64 s[6:7], s[28:29], s[0:1]
	v_mfma_f32_32x32x16_bf16 v[18:33], v[170:173], v[190:193], v[18:33]
	v_max_f32_e32 v4, v4, v4
	s_cmp_eq_u64 s[6:7], 0
	s_cselect_b64 vcc, -1, 0
	s_and_b64 s[34:35], s[26:27], s[0:1]
	s_cmp_eq_u64 s[34:35], 0
	s_cselect_b64 s[0:1], -1, 0
	s_or_b64 s[0:1], vcc, s[0:1]
	s_or_b64 s[0:1], s[0:1], s[10:11]
	v_mfma_f32_32x32x16_bf16 v[34:49], v[174:177], v[190:193], v[34:49]
	v_max_f32_e32 v2, v2, v2
	v_max_f32_e32 v2, v2, v4
	v_cmp_lt_f32_e32 vcc, s15, v2
	s_cbranch_vccnz .Lsel_shift_h
	s_cmp_eq_u32 s31, s22
	s_cbranch_scc1 .Lsel_fast_exit
	v_mov_b32_e32 v2, v252
	s_and_b32 s23, s9, 1
	s_cmp_eq_u64 s[0:1], 0
	s_mul_i32 s1, s23, 0x4800
	s_mul_i32 s0, s23, 0x1800
	s_cbranch_scc1 .Latt2_entry
	s_cmp_lg_u64 s[10:11], 0
	s_cbranch_scc1 .Lsel_generic
	s_cmp_lg_u64 s[6:7], 0
	s_cbranch_scc1 .Latt1a_entry
	s_cmp_lg_u64 s[34:35], 0
	s_cbranch_scc1 .Latt1b_entry
	s_branch .Lsel_none

.LBB0_2362:
	s_setprio 0
	v_readlane_b32 s0, v255, 40
	s_add_i32 s44, s0, 1
	v_readlane_b32 s0, v253, 5
	v_readlane_b32 s1, v253, 6
	s_cmp_lt_i32 s44, s1
	v_readlane_b32 s2, v255, 28
	s_cselect_b64 s[0:1], -1, 0
	v_readlane_b32 s3, v255, 29
	s_and_b64 s[0:1], s[2:3], s[0:1]
	s_and_b64 vcc, exec, s[0:1]
	v_readlane_b32 s64, v255, 32
	s_cbranch_vccz .LBB0_2412
	s_waitcnt vmcnt(0)
	s_waitcnt vmcnt(0)
	s_barrier
	s_mov_b64 s[2:3], exec
	v_readlane_b32 s0, v253, 2
	v_readlane_b32 s1, v253, 3
	s_and_b64 s[0:1], s[2:3], s[0:1]
	s_mov_b64 exec, s[0:1]
	s_cbranch_execz .LBB0_2411
	v_readlane_b32 s0, v253, 1
	s_waitcnt vmcnt(0) expcnt(0) lgkmcnt(0)
	s_nop 0
	v_mov_b32_e32 v1, s0
	ds_read_b32 v4, v1
	ds_read_b32 v2, v1 offset:4
	s_waitcnt lgkmcnt(1)
	v_cmp_ne_u32_e32 vcc, 0, v4
	s_cbranch_vccnz .LBB0_2379
	v_readlane_b32 s4, v253, 7
	v_readlane_b32 s5, v253, 8
	s_load_dwordx2 s[0:1], s[4:5], 0x0
	s_nop 0
	s_load_dword s4, s[4:5], 0x8
	s_waitcnt lgkmcnt(0)
	s_mul_i32 s0, s1, s0
	s_mul_i32 s0, s0, s4
	s_mov_b32 s1, 1
	s_branch .LBB0_2367
